# MLA K-tile load addresses from per-unit 64-bit bases + scalar tile offset
# baseline (speedup 1.0000x reference)
; #define ATT_BAR() do { asm volatile("s_waitcnt lgkmcnt(0)" ::: "memory"); __builtin_amdgcn_s_barrier(); asm volatile("" ::: "memory"); } while (0)
; template <int DK, int DV>
; __device__ __forceinline__ void attn_unit(LAS unsigned char* lds, const bf16* Qp, int ldq, const bf16* Kp, int ldk, const bf16* VTp, bf16* Op, int ldo, int qb) {
;     ...
;     ATT_LOAD(0, kra, vra); ATT_LOAD(1, krb, vrb);
;     ATT_STORE(0, kra, vra); ATT_STORE(BUF, krb, vrb);
;     ATT_LOAD(2, krb, vrb);
;     __syncthreads();
;     float mrun = 0.f, lrun = 0.f;
;     f32x16 o[NDB];
; #pragma unroll
;     for (int db = 0; db < NDB; ++db)
; #pragma unroll
;         for (int r = 0; r < 16; ++r) o[db][r] = 0.f;
;     f32x16 s0, s1;
;     const f32x16 zacc = {0.f, 0.f, 0.f, 0.f, 0.f, 0.f, 0.f, 0.f, 0.f, 0.f, 0.f, 0.f, 0.f, 0.f, 0.f, 0.f};
;     f32x16 negm = zacc;
;     constexpr float ATT_THR = 8.f;
;     ATT_QK(0, zacc);
;     if (grpB) ATT_BAR();
;     int bcur = 0, bnext = BUF, bfree = 2 * BUF;
.LBB0_1036:
	ds_read_b128 v[196:199], v141
	ds_read_b128 v[200:203], v141 offset:1024
	ds_read_b128 v[204:207], v141 offset:2048
	ds_read_b128 v[208:211], v141 offset:3072
	ds_read_b128 v[212:215], v141 offset:4096
	ds_read_b128 v[216:219], v141 offset:5120
	v_or_b32_e32 v159, s46, v6
	v_mul_u32_u24_e32 v6, 0x90, v6
	v_lshlrev_b32_e32 v158, 2, v7
	v_lshl_add_u64 v[144:145], v[2:3], 1, s[4:5]
	v_lshl_add_u64 v[146:147], v[4:5], 1, s[4:5]
	v_mad_i64_i32 v[186:187], vcc, v150, s3, v[144:145]
	v_mad_i64_i32 v[188:189], vcc, v151, s3, v[146:147]
	v_add3_u32 v160, 0, v6, v0
	v_mov_b32_e32 v2, v1
	v_mov_b32_e32 v3, v1
	v_mov_b32_e32 v4, v1
	v_mov_b32_e32 v5, v1
	v_mov_b32_e32 v6, v1
	v_mov_b32_e32 v7, v1
	v_mov_b32_e32 v8, v1
	v_mov_b32_e32 v9, v1
	v_mov_b32_e32 v10, v1
	v_mov_b32_e32 v11, v1
	v_mov_b32_e32 v12, v1
	v_mov_b32_e32 v13, v1
	v_mov_b32_e32 v14, v1
	v_mov_b32_e32 v15, v1
	v_mov_b32_e32 v16, v1
	v_mov_b32_e32 v17, v1
	v_mov_b32_e32 v18, v1
	v_mov_b32_e32 v19, v1
	v_mov_b32_e32 v20, v1
	v_mov_b32_e32 v21, v1
	v_mov_b32_e32 v22, v1
	v_mov_b32_e32 v23, v1
	v_mov_b32_e32 v24, v1
	v_mov_b32_e32 v25, v1
	v_mov_b32_e32 v26, v1
	v_mov_b32_e32 v27, v1
	v_mov_b32_e32 v28, v1
	v_mov_b32_e32 v29, v1
	v_mov_b32_e32 v30, v1
	v_mov_b32_e32 v31, v1
	s_lshl_b32 s48, s0, 2
	v_mov_b32_e32 v0, v1
	v_mov_b64_e32 v[32:33], v[30:31]
	s_lshl_b32 s47, s1, 13
	v_ashrrev_i32_e32 v139, 31, v138
	s_add_i32 s49, s48, 4
	s_or_b32 s50, s48, 3
	s_or_b32 s51, s46, 31
	s_mov_b32 s54, 0
	s_sub_i32 s55, 0, s48
	s_sub_i32 s56, 0, s8
	v_subrev_u32_e32 v161, s8, v158
	v_mov_b32_e32 v66, v1
	v_mov_b32_e32 v67, v1
	v_mov_b32_e32 v68, v1
	v_mov_b32_e32 v69, v1
	v_mov_b32_e32 v70, v1
	v_mov_b32_e32 v71, v1
	v_mov_b32_e32 v72, v1
	v_mov_b32_e32 v73, v1
	v_mov_b32_e32 v74, v1
	v_mov_b32_e32 v75, v1
	v_mov_b32_e32 v76, v1
	v_mov_b32_e32 v77, v1
	v_mov_b32_e32 v78, v1
	v_mov_b32_e32 v79, v1
	v_mov_b32_e32 v80, v1
	v_mov_b32_e32 v81, v1
	s_mov_b32 s57, 0xb000
	s_movk_i32 s58, 0x5800
	v_mov_b32_e32 v162, 0
	v_mov_b32_e32 v163, 0
	s_mov_b32 s0, 0
	s_mov_b32 s59, 0
	v_mov_b64_e32 v[30:31], v[28:29]
	v_mov_b64_e32 v[28:29], v[26:27]
	v_mov_b64_e32 v[26:27], v[24:25]
	v_mov_b64_e32 v[24:25], v[22:23]
	v_mov_b64_e32 v[22:23], v[20:21]
	v_mov_b64_e32 v[20:21], v[18:19]
	v_mov_b64_e32 v[18:19], v[16:17]
	v_mov_b64_e32 v[16:17], v[14:15]
	v_mov_b64_e32 v[14:15], v[12:13]
	v_mov_b64_e32 v[12:13], v[10:11]
	v_mov_b64_e32 v[10:11], v[8:9]
	v_mov_b64_e32 v[8:9], v[6:7]
	v_mov_b64_e32 v[6:7], v[4:5]
	v_mov_b64_e32 v[4:5], v[2:3]
	v_mov_b64_e32 v[2:3], v[0:1]
.LBB0_1037:
	s_add_i32 s1, s59, 3
	s_cmp_lt_u32 s1, s49
	s_cselect_b32 s1, s1, s50
	s_lshl_b32 s8, s1, 6
	s_mul_i32 s4, s8, 0x600
	s_mov_b32 s5, 0
	v_lshl_add_u64 v[94:95], s[4:5], 0, v[186:187]
	v_lshl_add_u64 v[96:97], s[4:5], 0, v[188:189]
	v_lshl_add_u64 v[102:103], s[8:9], 1, v[142:143]
	global_load_dwordx4 v[98:101], v[94:95], off
	s_nop 0
	global_load_dwordx4 v[94:97], v[96:97], off
	s_add_i32 s62, s55, s59
	global_load_dwordx4 v[102:105], v[102:103], off
	s_cmp_lt_i32 s62, 0
	s_cselect_b64 s[18:19], -1, 0
	s_add_i32 s61, s56, s54
	s_cmp_le_i32 s61, s51
	s_cselect_b64 s[4:5], -1, 0
	s_or_b64 s[20:21], s[18:19], s[4:5]
	s_mov_b32 s60, s58
	s_not_b64 s[4:5], s[20:21]
	s_andn2_b64 vcc, exec, s[20:21]
	s_mov_b32 s58, s0
	v_add_u32_e32 v248, s58, v160
	ds_read_b128 v[164:167], v248 offset:13312
	ds_read_b128 v[168:171], v248 offset:17920
	ds_read_b128 v[172:175], v248 offset:13344
	ds_read_b128 v[176:179], v248 offset:17952
	ds_read_b128 v[180:183], v248 offset:13376
	ds_read_b128 v[220:223], v248 offset:17984
	ds_read_b128 v[224:227], v248 offset:13408
	ds_read_b128 v[232:235], v248 offset:18016
	s_cbranch_vccnz .LBB0_1049
	s_cmp_lt_i32 s62, 0
	s_cbranch_scc0 .Lmla_a_mask

.LBB0_1053:
	s_setprio 0
	s_add_i32 s0, s59, 4
	s_cmp_lt_u32 s59, s48
	s_cselect_b32 s0, s0, s50
	s_lshl_b32 s8, s0, 6
	s_waitcnt lgkmcnt(0)
	s_barrier
	s_mul_i32 s0, s8, 0x600
	s_mov_b32 s1, 0
	v_lshl_add_u64 v[82:83], s[0:1], 0, v[186:187]
	v_lshl_add_u64 v[84:85], s[0:1], 0, v[188:189]
	global_load_dwordx4 v[86:89], v[82:83], off
	global_load_dwordx4 v[90:93], v[84:85], off
	v_lshl_add_u64 v[82:83], s[8:9], 1, v[142:143]
	global_load_dwordx4 v[82:85], v[82:83], off
	v_add_u32_e32 v248, s60, v160
	ds_read_b128 v[164:167], v248 offset:13312
	ds_read_b128 v[168:171], v248 offset:17920
	ds_read_b128 v[172:175], v248 offset:13344
	ds_read_b128 v[176:179], v248 offset:17952
	ds_read_b128 v[180:183], v248 offset:13376
	ds_read_b128 v[220:223], v248 offset:17984
	ds_read_b128 v[224:227], v248 offset:13408
	ds_read_b128 v[232:235], v248 offset:18016
	s_add_i32 s62, s62, 1
	s_cmp_lt_i32 s62, 0
	s_cselect_b64 s[0:1], -1, 0
	s_add_i32 s4, s61, 64
	s_cmp_le_i32 s4, s51
	s_cselect_b64 s[4:5], -1, 0
	s_or_b64 s[0:1], s[0:1], s[4:5]
	s_not_b64 s[4:5], s[0:1]
	s_andn2_b64 vcc, exec, s[0:1]
	s_cbranch_vccnz .LBB0_1059
	s_cmp_lt_i32 s62, 0
	s_cbranch_scc0 .Lmla_b_mask
